# attention unit order per workgroup 31-j, j, 23-j, j+8: the eight workgroups sharing a head's K/V re-align at the third unit (L2 sharing of K/V tiles)
# baseline (speedup 1.0000x reference)
.LBB0_1333:
	s_cmp_lt_i32 s96, 1
	s_mov_b32 s4, s89
	s_cbranch_scc1 .LBB0_1338
	s_cmp_lg_u32 s96, 1
	s_mov_b64 s[0:1], -1
	s_cbranch_scc0 .LBB0_1336
	s_cmp_eq_u32 s96, 2
	s_cselect_b32 s4, s88, s90
	s_mov_b64 s[0:1], 0
.LBB0_1336:
	s_andn2_b64 vcc, exec, s[0:1]
	s_cbranch_vccnz .LBB0_1338
	s_mov_b32 s4, s87
